# SwiGLU epilogue stores of the hidden buffer made write-through (sc0 sc1 instead of nt) so the grid barrier's L2 write-back has less dirty data
# baseline (speedup 1.0000x reference)
; #define LAS __attribute__((address_space(3)))
; __device__ __forceinline__ unsigned pk2(float lo, float hi) { unsigned r; asm("v_cvt_pk_bf16_f32 %0, %1, %2" : "=v"(r) : "v"(lo), "v"(hi)); return r; }
;     __device__ __forceinline__ void operator()(const f32x4 (&acc)[2][2][4][2], const pg8::Unit& u, int wr, int wc, int fr_, int fq_) const {
;     ...
;         const int s = u.pm < 128 ? (u.pm >> 5) : 4;
;         const int row0 = u.pm * 256 + wr * 64 + fr, jc = u.pn * 128 + wc * 32 + fq * 8;
;         const LAS float* swp = vtab + u.ui * 256 + wc * 32 + fq * 8;
;         const f32x4 g0 = *(const LAS f32x4*)swp, g1 = *(const LAS f32x4*)(swp + 4), u0 = *(const LAS f32x4*)(swp + 128), u1 = *(const LAS f32x4*)(swp + 132);
;         float rs[2][4]; rows_rstd(rtab, u.ui, wr * 64 + fr, rs);
; #pragma unroll
;         for (int ai = 0; ai < 2; ++ai)
; #pragma unroll
;             for (int m = 0; m < 4; ++m) {
;                 const int row = row0 + ai * 128 + m * 16; const float rstd = rs[ai][m];
;                 f32x4 g[2], up[2], e[2];
;                 g[0] = acc[ai][0][m][0] * rstd + g0; g[1] = acc[ai][0][m][1] * rstd + g1; up[0] = acc[ai][1][m][0] * rstd + u0; up[1] = acc[ai][1][m][1] * rstd + u1;
; #pragma unroll
;                 for (int h = 0; h < 2; ++h) { const f32x4 t = g[h] * -1.4426950408889634f;
;                     e[h] = (f32x4){__builtin_amdgcn_exp2f(t.x), __builtin_amdgcn_exp2f(t.y), __builtin_amdgcn_exp2f(t.z), __builtin_amdgcn_exp2f(t.w)}; }
; #pragma unroll
;                 for (int h = 0; h < 2; ++h) { const f32x4 d = e[h] + 1.0f;
;                     e[h] = (f32x4){__builtin_amdgcn_rcpf(d.x), __builtin_amdgcn_rcpf(d.y), __builtin_amdgcn_rcpf(d.z), __builtin_amdgcn_rcpf(d.w)}; }
; #pragma unroll
;                 for (int h = 0; h < 2; ++h) g[h] = (g[h] * up[h]) * e[h];
;                 u32x4 w; w.x = pk2(g[0].x, g[0].y); w.y = pk2(g[0].z, g[0].w); w.z = pk2(g[1].x, g[1].y); w.w = pk2(g[1].z, g[1].w);
;                 __builtin_nontemporal_store(w, (u32x4*)(hid + (size_t)row * DFF + jc));
.LBB0_747:
	s_lshl_b32 s17, s33, 7
	v_mov_b32_e32 v128, v161
	v_mov_b32_e32 v164, v160
	s_or_b32 s17, s17, s35
	s_lshl_b32 s3, s3, 10
	s_lshl_b32 s15, s43, 8
	v_lshl_add_u32 v166, v128, 3, s17
	s_add_i32 s17, s40, s3
	s_add_i32 s3, s41, s3
	v_lshl_add_u32 v132, v128, 5, s17
	v_lshl_add_u32 v154, v164, 2, s3
	ds_read_b128 v[140:143], v132
	ds_read_b128 v[136:139], v132 offset:16
	ds_read_b128 v[128:131], v132 offset:512
	ds_read_b128 v[132:135], v132 offset:528
	ds_read2_b32 v[168:169], v154 offset1:16
	ds_read2_b32 v[158:159], v154 offset0:32 offset1:48
	ds_read2_b32 v[156:157], v154 offset0:128 offset1:144
	ds_read2_b32 v[154:155], v154 offset0:160 offset1:176
	s_add_i32 s15, s15, s34
	s_waitcnt lgkmcnt(0)
	v_pk_fma_f32 v[124:125], v[124:125], v[168:169], v[140:141] op_sel_hi:[1,0,1]
	v_pk_fma_f32 v[126:127], v[126:127], v[168:169], v[142:143] op_sel_hi:[1,0,1]
	v_pk_fma_f32 v[120:121], v[120:121], v[168:169], v[136:137] op_sel_hi:[1,0,1]
	v_pk_fma_f32 v[122:123], v[122:123], v[168:169], v[138:139] op_sel_hi:[1,0,1]
	v_pk_mul_f32 v[172:173], v[124:125], s[80:81] op_sel_hi:[1,0]
	v_pk_mul_f32 v[170:171], v[126:127], s[80:81] op_sel_hi:[1,0]
	v_exp_f32_e32 v172, v172
	v_exp_f32_e32 v173, v173
	v_pk_mul_f32 v[174:175], v[122:123], s[80:81] op_sel_hi:[1,0]
	v_pk_mul_f32 v[176:177], v[120:121], s[80:81] op_sel_hi:[1,0]
	v_exp_f32_e32 v170, v170
	v_exp_f32_e32 v171, v171
	v_exp_f32_e32 v176, v176
	v_exp_f32_e32 v177, v177
	v_exp_f32_e32 v174, v174
	v_exp_f32_e32 v175, v175
	v_pk_add_f32 v[172:173], v[172:173], 1.0 op_sel_hi:[1,0]
	v_pk_add_f32 v[170:171], v[170:171], 1.0 op_sel_hi:[1,0]
	v_rcp_f32_e32 v172, v172
	v_rcp_f32_e32 v173, v173
	v_pk_add_f32 v[174:175], v[174:175], 1.0 op_sel_hi:[1,0]
	v_pk_add_f32 v[176:177], v[176:177], 1.0 op_sel_hi:[1,0]
	v_rcp_f32_e32 v170, v170
	v_rcp_f32_e32 v171, v171
	v_rcp_f32_e32 v176, v176
	v_rcp_f32_e32 v177, v177
	v_rcp_f32_e32 v174, v174
	v_rcp_f32_e32 v175, v175
	v_pk_fma_f32 v[112:113], v[112:113], v[168:169], v[128:129] op_sel_hi:[1,0,1]
	v_pk_fma_f32 v[118:119], v[118:119], v[168:169], v[134:135] op_sel_hi:[1,0,1]
	v_pk_fma_f32 v[116:117], v[116:117], v[168:169], v[132:133] op_sel_hi:[1,0,1]
	v_pk_fma_f32 v[114:115], v[114:115], v[168:169], v[130:131] op_sel_hi:[1,0,1]
	v_pk_mul_f32 v[112:113], v[124:125], v[112:113]
	v_pk_mul_f32 v[114:115], v[126:127], v[114:115]
	v_pk_mul_f32 v[112:113], v[112:113], v[172:173]
	v_pk_mul_f32 v[116:117], v[120:121], v[116:117]
	v_pk_mul_f32 v[118:119], v[122:123], v[118:119]
	v_add_u32_e32 v164, s15, v164
	v_ashrrev_i32_e32 v167, 31, v166
	v_pk_mul_f32 v[114:115], v[114:115], v[170:171]
	v_pk_mul_f32 v[120:121], v[118:119], v[174:175]
	v_pk_mul_f32 v[118:119], v[116:117], v[176:177]
	v_cvt_pk_bf16_f32 v116, v112, v113
	v_mov_b64_e32 v[112:113], s[82:83]
	v_cvt_pk_bf16_f32 v117, v114, v115
	v_cvt_pk_bf16_f32 v118, v118, v119
	v_cvt_pk_bf16_f32 v119, v120, v121
	v_mad_i64_i32 v[120:121], s[22:23], v164, s91, v[112:113]
	v_lshlrev_b64 v[114:115], 1, v[166:167]
	v_lshl_add_u64 v[120:121], v[120:121], 0, v[114:115]
	global_store_dwordx4 v[120:121], v[116:119], off sc0 sc1
	v_pk_fma_f32 v[92:93], v[92:93], v[158:159], v[140:141] op_sel_hi:[1,0,1]
	v_pk_fma_f32 v[94:95], v[94:95], v[158:159], v[142:143] op_sel_hi:[1,0,1]
	v_mov_b32_e32 v116, v169
	v_pk_fma_f32 v[108:109], v[108:109], v[116:117], v[140:141] op_sel_hi:[1,0,1]
	v_pk_fma_f32 v[110:111], v[110:111], v[116:117], v[142:143] op_sel_hi:[1,0,1]
	v_pk_fma_f32 v[104:105], v[104:105], v[116:117], v[136:137] op_sel_hi:[1,0,1]
	v_pk_fma_f32 v[106:107], v[106:107], v[116:117], v[138:139] op_sel_hi:[1,0,1]
	v_pk_mul_f32 v[118:119], v[110:111], s[80:81] op_sel_hi:[1,0]
	v_pk_mul_f32 v[120:121], v[108:109], s[80:81] op_sel_hi:[1,0]
	v_pk_mul_f32 v[122:123], v[106:107], s[80:81] op_sel_hi:[1,0]
	v_pk_mul_f32 v[124:125], v[104:105], s[80:81] op_sel_hi:[1,0]
	v_exp_f32_e32 v120, v120
	v_exp_f32_e32 v121, v121
	v_exp_f32_e32 v118, v118
	v_exp_f32_e32 v119, v119
	v_exp_f32_e32 v124, v124
	v_exp_f32_e32 v125, v125
	v_exp_f32_e32 v122, v122
	v_exp_f32_e32 v123, v123
	v_pk_fma_f32 v[102:103], v[102:103], v[116:117], v[134:135] op_sel_hi:[1,0,1]
	v_pk_fma_f32 v[100:101], v[100:101], v[116:117], v[132:133] op_sel_hi:[1,0,1]
	v_pk_fma_f32 v[98:99], v[98:99], v[116:117], v[130:131] op_sel_hi:[1,0,1]
	v_pk_fma_f32 v[96:97], v[96:97], v[116:117], v[128:129] op_sel_hi:[1,0,1]
	v_pk_add_f32 v[116:117], v[118:119], 1.0 op_sel_hi:[1,0]
	v_pk_add_f32 v[118:119], v[120:121], 1.0 op_sel_hi:[1,0]
	v_pk_add_f32 v[120:121], v[122:123], 1.0 op_sel_hi:[1,0]
	v_pk_add_f32 v[122:123], v[124:125], 1.0 op_sel_hi:[1,0]
	v_rcp_f32_e32 v118, v118
	v_rcp_f32_e32 v119, v119
	v_rcp_f32_e32 v116, v116
	v_rcp_f32_e32 v117, v117
	v_rcp_f32_e32 v122, v122
	v_rcp_f32_e32 v123, v123
	v_rcp_f32_e32 v120, v120
	v_rcp_f32_e32 v121, v121
	v_pk_mul_f32 v[96:97], v[108:109], v[96:97]
	v_pk_mul_f32 v[98:99], v[110:111], v[98:99]
	v_pk_mul_f32 v[100:101], v[104:105], v[100:101]
	v_pk_mul_f32 v[98:99], v[98:99], v[116:117]
	v_pk_mul_f32 v[96:97], v[96:97], v[118:119]
	v_pk_mul_f32 v[100:101], v[100:101], v[122:123]
	v_add_u32_e32 v104, 16, v164
	v_pk_mul_f32 v[102:103], v[106:107], v[102:103]
	v_cvt_pk_bf16_f32 v96, v96, v97
	v_cvt_pk_bf16_f32 v97, v98, v99
	v_cvt_pk_bf16_f32 v98, v100, v101
	v_mad_i64_i32 v[100:101], s[22:23], v104, s91, v[112:113]
	v_pk_mul_f32 v[102:103], v[102:103], v[120:121]
	v_lshl_add_u64 v[100:101], v[100:101], 0, v[114:115]
	v_cvt_pk_bf16_f32 v99, v102, v103
	v_pk_fma_f32 v[88:89], v[88:89], v[158:159], v[136:137] op_sel_hi:[1,0,1]
	global_store_dwordx4 v[100:101], v[96:99], off sc0 sc1
	v_pk_mul_f32 v[102:103], v[88:89], s[80:81] op_sel_hi:[1,0]
; __device__ __forceinline__ unsigned pk2(float lo, float hi) { unsigned r; asm("v_cvt_pk_bf16_f32 %0, %1, %2" : "=v"(r) : "v"(lo), "v"(hi)); return r; }
;     __device__ __forceinline__ void operator()(const f32x4 (&acc)[2][2][4][2], const pg8::Unit& u, int wr, int wc, int fr_, int fq_) const {
;     ...
;                 const int row = row0 + ai * 128 + m * 16; const float rstd = rs[ai][m];
;                 f32x4 g[2], up[2], e[2];
;                 g[0] = acc[ai][0][m][0] * rstd + g0; g[1] = acc[ai][0][m][1] * rstd + g1; up[0] = acc[ai][1][m][0] * rstd + u0; up[1] = acc[ai][1][m][1] * rstd + u1;
; #pragma unroll
;                 for (int h = 0; h < 2; ++h) { const f32x4 t = g[h] * -1.4426950408889634f;
;                     e[h] = (f32x4){__builtin_amdgcn_exp2f(t.x), __builtin_amdgcn_exp2f(t.y), __builtin_amdgcn_exp2f(t.z), __builtin_amdgcn_exp2f(t.w)}; }
; #pragma unroll
;                 for (int h = 0; h < 2; ++h) { const f32x4 d = e[h] + 1.0f;
;                     e[h] = (f32x4){__builtin_amdgcn_rcpf(d.x), __builtin_amdgcn_rcpf(d.y), __builtin_amdgcn_rcpf(d.z), __builtin_amdgcn_rcpf(d.w)}; }
; #pragma unroll
;                 for (int h = 0; h < 2; ++h) g[h] = (g[h] * up[h]) * e[h];
;                 u32x4 w; w.x = pk2(g[0].x, g[0].y); w.y = pk2(g[0].z, g[0].w); w.z = pk2(g[1].x, g[1].y); w.w = pk2(g[1].z, g[1].w);
;                 __builtin_nontemporal_store(w, (u32x4*)(hid + (size_t)row * DFF + jc));
	v_pk_fma_f32 v[90:91], v[90:91], v[158:159], v[138:139] op_sel_hi:[1,0,1]
	v_pk_mul_f32 v[96:97], v[94:95], s[80:81] op_sel_hi:[1,0]
	v_pk_mul_f32 v[98:99], v[92:93], s[80:81] op_sel_hi:[1,0]
	v_exp_f32_e32 v96, v96
	v_exp_f32_e32 v98, v98
	v_exp_f32_e32 v99, v99
	v_exp_f32_e32 v97, v97
	v_exp_f32_e32 v102, v102
	v_exp_f32_e32 v103, v103
	v_pk_mul_f32 v[100:101], v[90:91], s[80:81] op_sel_hi:[1,0]
	v_pk_add_f32 v[96:97], v[96:97], 1.0 op_sel_hi:[1,0]
	v_exp_f32_e32 v100, v100
	v_exp_f32_e32 v101, v101
	v_pk_add_f32 v[98:99], v[98:99], 1.0 op_sel_hi:[1,0]
	v_pk_add_f32 v[102:103], v[102:103], 1.0 op_sel_hi:[1,0]
	v_rcp_f32_e32 v98, v98
	v_rcp_f32_e32 v99, v99
	v_rcp_f32_e32 v96, v96
	v_rcp_f32_e32 v97, v97
	v_rcp_f32_e32 v102, v102
	v_rcp_f32_e32 v103, v103
	v_pk_fma_f32 v[84:85], v[84:85], v[158:159], v[132:133] op_sel_hi:[1,0,1]
	v_pk_fma_f32 v[82:83], v[82:83], v[158:159], v[130:131] op_sel_hi:[1,0,1]
	v_pk_fma_f32 v[80:81], v[80:81], v[158:159], v[128:129] op_sel_hi:[1,0,1]
	v_pk_add_f32 v[100:101], v[100:101], 1.0 op_sel_hi:[1,0]
	v_pk_mul_f32 v[80:81], v[92:93], v[80:81]
	v_rcp_f32_e32 v100, v100
	v_rcp_f32_e32 v101, v101
	v_pk_mul_f32 v[82:83], v[94:95], v[82:83]
	v_pk_mul_f32 v[84:85], v[88:89], v[84:85]
	v_pk_mul_f32 v[82:83], v[82:83], v[96:97]
	v_pk_mul_f32 v[80:81], v[80:81], v[98:99]
	v_pk_mul_f32 v[84:85], v[84:85], v[102:103]
	v_add_u32_e32 v88, 32, v164
	v_pk_fma_f32 v[86:87], v[86:87], v[158:159], v[134:135] op_sel_hi:[1,0,1]
	v_cvt_pk_bf16_f32 v80, v80, v81
	v_cvt_pk_bf16_f32 v81, v82, v83
	v_cvt_pk_bf16_f32 v82, v84, v85
	v_mad_i64_i32 v[84:85], s[22:23], v88, s91, v[112:113]
	v_pk_mul_f32 v[86:87], v[90:91], v[86:87]
	v_lshl_add_u64 v[84:85], v[84:85], 0, v[114:115]
	v_pk_mul_f32 v[86:87], v[86:87], v[100:101]
	v_pk_fma_f32 v[60:61], v[60:61], v[156:157], v[140:141] op_sel_hi:[1,0,1]
	v_cvt_pk_bf16_f32 v83, v86, v87
	global_store_dwordx4 v[84:85], v[80:83], off sc0 sc1
	v_pk_fma_f32 v[62:63], v[62:63], v[156:157], v[142:143] op_sel_hi:[1,0,1]
	v_pk_fma_f32 v[56:57], v[56:57], v[156:157], v[136:137] op_sel_hi:[1,0,1]
	v_mov_b32_e32 v80, v159
	v_pk_fma_f32 v[76:77], v[76:77], v[80:81], v[140:141] op_sel_hi:[1,0,1]
	v_pk_fma_f32 v[78:79], v[78:79], v[80:81], v[142:143] op_sel_hi:[1,0,1]
	v_pk_fma_f32 v[72:73], v[72:73], v[80:81], v[136:137] op_sel_hi:[1,0,1]
	v_pk_fma_f32 v[74:75], v[74:75], v[80:81], v[138:139] op_sel_hi:[1,0,1]
	v_pk_mul_f32 v[82:83], v[78:79], s[80:81] op_sel_hi:[1,0]
	v_pk_mul_f32 v[84:85], v[76:77], s[80:81] op_sel_hi:[1,0]
	v_pk_mul_f32 v[86:87], v[74:75], s[80:81] op_sel_hi:[1,0]
	v_pk_mul_f32 v[88:89], v[72:73], s[80:81] op_sel_hi:[1,0]
	v_exp_f32_e32 v84, v84
	v_exp_f32_e32 v85, v85
	v_exp_f32_e32 v82, v82
	v_exp_f32_e32 v83, v83
	v_exp_f32_e32 v88, v88
	v_exp_f32_e32 v89, v89
	v_exp_f32_e32 v86, v86
	v_exp_f32_e32 v87, v87
	v_pk_fma_f32 v[70:71], v[70:71], v[80:81], v[134:135] op_sel_hi:[1,0,1]
	v_pk_fma_f32 v[68:69], v[68:69], v[80:81], v[132:133] op_sel_hi:[1,0,1]
	v_pk_fma_f32 v[66:67], v[66:67], v[80:81], v[130:131] op_sel_hi:[1,0,1]
	v_pk_fma_f32 v[64:65], v[64:65], v[80:81], v[128:129] op_sel_hi:[1,0,1]
	v_pk_add_f32 v[80:81], v[82:83], 1.0 op_sel_hi:[1,0]
	v_pk_add_f32 v[82:83], v[84:85], 1.0 op_sel_hi:[1,0]
	v_pk_add_f32 v[84:85], v[86:87], 1.0 op_sel_hi:[1,0]
	v_pk_add_f32 v[86:87], v[88:89], 1.0 op_sel_hi:[1,0]
	v_rcp_f32_e32 v82, v82
	v_rcp_f32_e32 v83, v83
	v_rcp_f32_e32 v80, v80
	v_rcp_f32_e32 v81, v81
	v_rcp_f32_e32 v86, v86
	v_rcp_f32_e32 v87, v87
	v_rcp_f32_e32 v84, v84
	v_rcp_f32_e32 v85, v85
	v_pk_mul_f32 v[64:65], v[76:77], v[64:65]
	v_pk_mul_f32 v[66:67], v[78:79], v[66:67]
	v_pk_mul_f32 v[68:69], v[72:73], v[68:69]
	v_pk_mul_f32 v[66:67], v[66:67], v[80:81]
	v_pk_mul_f32 v[64:65], v[64:65], v[82:83]
	v_pk_mul_f32 v[68:69], v[68:69], v[86:87]
	v_add_u32_e32 v72, 48, v164
	v_pk_mul_f32 v[70:71], v[74:75], v[70:71]
	v_cvt_pk_bf16_f32 v64, v64, v65
	v_cvt_pk_bf16_f32 v65, v66, v67
	v_cvt_pk_bf16_f32 v66, v68, v69
	v_mad_i64_i32 v[68:69], s[22:23], v72, s91, v[112:113]
	v_pk_mul_f32 v[70:71], v[70:71], v[84:85]
	v_lshl_add_u64 v[68:69], v[68:69], 0, v[114:115]
	v_cvt_pk_bf16_f32 v67, v70, v71
	global_store_dwordx4 v[68:69], v[64:67], off sc0 sc1
	v_pk_mul_f32 v[70:71], v[56:57], s[80:81] op_sel_hi:[1,0]
	v_pk_fma_f32 v[58:59], v[58:59], v[156:157], v[138:139] op_sel_hi:[1,0,1]
	v_pk_mul_f32 v[64:65], v[62:63], s[80:81] op_sel_hi:[1,0]
	v_pk_mul_f32 v[66:67], v[60:61], s[80:81] op_sel_hi:[1,0]
	v_exp_f32_e32 v64, v64
	v_exp_f32_e32 v66, v66
	v_exp_f32_e32 v67, v67
	v_exp_f32_e32 v65, v65
	v_exp_f32_e32 v70, v70
	v_exp_f32_e32 v71, v71
	v_pk_mul_f32 v[68:69], v[58:59], s[80:81] op_sel_hi:[1,0]
	v_pk_add_f32 v[64:65], v[64:65], 1.0 op_sel_hi:[1,0]
	v_exp_f32_e32 v68, v68
	v_exp_f32_e32 v69, v69
	v_pk_add_f32 v[66:67], v[66:67], 1.0 op_sel_hi:[1,0]
	v_pk_add_f32 v[70:71], v[70:71], 1.0 op_sel_hi:[1,0]
	v_rcp_f32_e32 v66, v66
	v_rcp_f32_e32 v67, v67
	v_rcp_f32_e32 v64, v64
	v_rcp_f32_e32 v65, v65
	v_rcp_f32_e32 v70, v70
	v_rcp_f32_e32 v71, v71
	v_pk_fma_f32 v[52:53], v[52:53], v[156:157], v[132:133] op_sel_hi:[1,0,1]
	v_pk_fma_f32 v[50:51], v[50:51], v[156:157], v[130:131] op_sel_hi:[1,0,1]
	v_pk_fma_f32 v[48:49], v[48:49], v[156:157], v[128:129] op_sel_hi:[1,0,1]
	v_pk_add_f32 v[68:69], v[68:69], 1.0 op_sel_hi:[1,0]
	v_pk_mul_f32 v[48:49], v[60:61], v[48:49]
	v_rcp_f32_e32 v68, v68
	v_rcp_f32_e32 v69, v69
	v_pk_mul_f32 v[50:51], v[62:63], v[50:51]
	v_pk_mul_f32 v[52:53], v[56:57], v[52:53]
	v_add_u32_e32 v72, 0x80, v164
	v_pk_mul_f32 v[50:51], v[50:51], v[64:65]
	v_pk_mul_f32 v[48:49], v[48:49], v[66:67]
	v_pk_mul_f32 v[52:53], v[52:53], v[70:71]
; #define PG8_BAR __builtin_amdgcn_s_barrier()
; __device__ __forceinline__ unsigned pk2(float lo, float hi) { unsigned r; asm("v_cvt_pk_bf16_f32 %0, %1, %2" : "=v"(r) : "v"(lo), "v"(hi)); return r; }
; template <class Epi, class Sched>
; __device__ __forceinline__ void gemm_phase(LAS unsigned char* lds, const Gemm g, const Sched& S, const Epi& E) {
;     ...
;         if (!has_next) break;
; #pragma unroll
;         for (int a = 0; a < 2; ++a)
; #pragma unroll
;             for (int b = 0; b < 2; ++b)
; #pragma unroll
;                 for (int m = 0; m < 4; ++m)
; #pragma unroll
;                     for (int n = 0; n < 2; ++n) acc[a][b][m][n] = (f32x4){0.f, 0.f, 0.f, 0.f};
;         cur = nxt; cA = nA; cB = nB; ++ui;
;         if (wr == 1) PG8_BAR;
;     __device__ __forceinline__ void operator()(const f32x4 (&acc)[2][2][4][2], const pg8::Unit& u, int wr, int wc, int fr_, int fq_) const {
;     ...
;                 const int row = row0 + ai * 128 + m * 16; const float rstd = rs[ai][m];
;                 f32x4 g[2], up[2], e[2];
;                 g[0] = acc[ai][0][m][0] * rstd + g0; g[1] = acc[ai][0][m][1] * rstd + g1; up[0] = acc[ai][1][m][0] * rstd + u0; up[1] = acc[ai][1][m][1] * rstd + u1;
; #pragma unroll
;                 for (int h = 0; h < 2; ++h) { const f32x4 t = g[h] * -1.4426950408889634f;
;                     e[h] = (f32x4){__builtin_amdgcn_exp2f(t.x), __builtin_amdgcn_exp2f(t.y), __builtin_amdgcn_exp2f(t.z), __builtin_amdgcn_exp2f(t.w)}; }
; #pragma unroll
;                 for (int h = 0; h < 2; ++h) { const f32x4 d = e[h] + 1.0f;
;                     e[h] = (f32x4){__builtin_amdgcn_rcpf(d.x), __builtin_amdgcn_rcpf(d.y), __builtin_amdgcn_rcpf(d.z), __builtin_amdgcn_rcpf(d.w)}; }
; #pragma unroll
;                 for (int h = 0; h < 2; ++h) g[h] = (g[h] * up[h]) * e[h];
;                 u32x4 w; w.x = pk2(g[0].x, g[0].y); w.y = pk2(g[0].z, g[0].w); w.z = pk2(g[1].x, g[1].y); w.w = pk2(g[1].z, g[1].w);
;                 __builtin_nontemporal_store(w, (u32x4*)(hid + (size_t)row * DFF + jc));
	v_pk_fma_f32 v[54:55], v[54:55], v[156:157], v[134:135] op_sel_hi:[1,0,1]
	v_cvt_pk_bf16_f32 v48, v48, v49
	v_cvt_pk_bf16_f32 v49, v50, v51
	v_cvt_pk_bf16_f32 v50, v52, v53
	v_mad_i64_i32 v[52:53], s[22:23], v72, s91, v[112:113]
	v_pk_mul_f32 v[54:55], v[58:59], v[54:55]
	v_lshl_add_u64 v[52:53], v[52:53], 0, v[114:115]
	v_pk_mul_f32 v[54:55], v[54:55], v[68:69]
	v_pk_fma_f32 v[28:29], v[28:29], v[154:155], v[140:141] op_sel_hi:[1,0,1]
	v_cvt_pk_bf16_f32 v51, v54, v55
	global_store_dwordx4 v[52:53], v[48:51], off sc0 sc1
	v_pk_fma_f32 v[30:31], v[30:31], v[154:155], v[142:143] op_sel_hi:[1,0,1]
	v_pk_fma_f32 v[24:25], v[24:25], v[154:155], v[136:137] op_sel_hi:[1,0,1]
	v_mov_b32_e32 v48, v157
	v_pk_fma_f32 v[44:45], v[44:45], v[48:49], v[140:141] op_sel_hi:[1,0,1]
	v_pk_fma_f32 v[46:47], v[46:47], v[48:49], v[142:143] op_sel_hi:[1,0,1]
	v_pk_fma_f32 v[40:41], v[40:41], v[48:49], v[136:137] op_sel_hi:[1,0,1]
	v_pk_fma_f32 v[42:43], v[42:43], v[48:49], v[138:139] op_sel_hi:[1,0,1]
	v_pk_mul_f32 v[50:51], v[46:47], s[80:81] op_sel_hi:[1,0]
	v_pk_mul_f32 v[52:53], v[44:45], s[80:81] op_sel_hi:[1,0]
	v_pk_mul_f32 v[54:55], v[42:43], s[80:81] op_sel_hi:[1,0]
	v_pk_mul_f32 v[56:57], v[40:41], s[80:81] op_sel_hi:[1,0]
	v_exp_f32_e32 v52, v52
	v_exp_f32_e32 v53, v53
	v_exp_f32_e32 v50, v50
	v_exp_f32_e32 v51, v51
	v_exp_f32_e32 v56, v56
	v_exp_f32_e32 v57, v57
	v_exp_f32_e32 v54, v54
	v_exp_f32_e32 v55, v55
	v_pk_fma_f32 v[38:39], v[38:39], v[48:49], v[134:135] op_sel_hi:[1,0,1]
	v_pk_fma_f32 v[36:37], v[36:37], v[48:49], v[132:133] op_sel_hi:[1,0,1]
	v_pk_fma_f32 v[34:35], v[34:35], v[48:49], v[130:131] op_sel_hi:[1,0,1]
	v_pk_fma_f32 v[32:33], v[32:33], v[48:49], v[128:129] op_sel_hi:[1,0,1]
	v_pk_add_f32 v[48:49], v[50:51], 1.0 op_sel_hi:[1,0]
	v_pk_add_f32 v[50:51], v[52:53], 1.0 op_sel_hi:[1,0]
	v_pk_add_f32 v[52:53], v[54:55], 1.0 op_sel_hi:[1,0]
	v_pk_add_f32 v[54:55], v[56:57], 1.0 op_sel_hi:[1,0]
	v_rcp_f32_e32 v50, v50
	v_rcp_f32_e32 v51, v51
	v_rcp_f32_e32 v48, v48
	v_rcp_f32_e32 v49, v49
	v_rcp_f32_e32 v54, v54
	v_rcp_f32_e32 v55, v55
	v_rcp_f32_e32 v52, v52
	v_rcp_f32_e32 v53, v53
	v_pk_mul_f32 v[32:33], v[44:45], v[32:33]
	v_pk_mul_f32 v[34:35], v[46:47], v[34:35]
	v_pk_mul_f32 v[36:37], v[40:41], v[36:37]
	v_pk_mul_f32 v[34:35], v[34:35], v[48:49]
	v_pk_mul_f32 v[32:33], v[32:33], v[50:51]
	v_pk_mul_f32 v[36:37], v[36:37], v[54:55]
	v_add_u32_e32 v40, 0x90, v164
	v_pk_mul_f32 v[38:39], v[42:43], v[38:39]
	v_cvt_pk_bf16_f32 v32, v32, v33
	v_cvt_pk_bf16_f32 v33, v34, v35
	v_cvt_pk_bf16_f32 v34, v36, v37
	v_mad_i64_i32 v[36:37], s[22:23], v40, s91, v[112:113]
	v_pk_mul_f32 v[38:39], v[38:39], v[52:53]
	v_lshl_add_u64 v[36:37], v[36:37], 0, v[114:115]
	v_cvt_pk_bf16_f32 v35, v38, v39
	global_store_dwordx4 v[36:37], v[32:35], off sc0 sc1
	v_pk_mul_f32 v[38:39], v[24:25], s[80:81] op_sel_hi:[1,0]
	v_pk_fma_f32 v[26:27], v[26:27], v[154:155], v[138:139] op_sel_hi:[1,0,1]
	v_pk_mul_f32 v[32:33], v[30:31], s[80:81] op_sel_hi:[1,0]
	v_pk_mul_f32 v[34:35], v[28:29], s[80:81] op_sel_hi:[1,0]
	v_exp_f32_e32 v32, v32
	v_exp_f32_e32 v34, v34
	v_exp_f32_e32 v35, v35
	v_exp_f32_e32 v33, v33
	v_exp_f32_e32 v38, v38
	v_exp_f32_e32 v39, v39
	v_pk_mul_f32 v[36:37], v[26:27], s[80:81] op_sel_hi:[1,0]
	v_pk_add_f32 v[32:33], v[32:33], 1.0 op_sel_hi:[1,0]
	v_exp_f32_e32 v36, v36
	v_exp_f32_e32 v37, v37
	v_pk_add_f32 v[34:35], v[34:35], 1.0 op_sel_hi:[1,0]
	v_pk_add_f32 v[38:39], v[38:39], 1.0 op_sel_hi:[1,0]
	v_rcp_f32_e32 v34, v34
	v_rcp_f32_e32 v35, v35
	v_rcp_f32_e32 v32, v32
	v_rcp_f32_e32 v33, v33
	v_rcp_f32_e32 v38, v38
	v_rcp_f32_e32 v39, v39
	v_pk_fma_f32 v[20:21], v[20:21], v[154:155], v[132:133] op_sel_hi:[1,0,1]
	v_pk_fma_f32 v[18:19], v[18:19], v[154:155], v[130:131] op_sel_hi:[1,0,1]
	v_pk_fma_f32 v[16:17], v[16:17], v[154:155], v[128:129] op_sel_hi:[1,0,1]
	v_pk_add_f32 v[36:37], v[36:37], 1.0 op_sel_hi:[1,0]
	v_pk_mul_f32 v[16:17], v[28:29], v[16:17]
	v_rcp_f32_e32 v36, v36
	v_rcp_f32_e32 v37, v37
	v_pk_mul_f32 v[18:19], v[30:31], v[18:19]
	v_pk_mul_f32 v[20:21], v[24:25], v[20:21]
	v_pk_mul_f32 v[18:19], v[18:19], v[32:33]
	v_pk_mul_f32 v[16:17], v[16:17], v[34:35]
	v_pk_mul_f32 v[20:21], v[20:21], v[38:39]
	v_add_u32_e32 v24, 0xa0, v164
	v_pk_fma_f32 v[22:23], v[22:23], v[154:155], v[134:135] op_sel_hi:[1,0,1]
	v_cvt_pk_bf16_f32 v16, v16, v17
	v_cvt_pk_bf16_f32 v17, v18, v19
	v_cvt_pk_bf16_f32 v18, v20, v21
	v_mad_i64_i32 v[20:21], s[22:23], v24, s91, v[112:113]
	v_pk_mul_f32 v[22:23], v[26:27], v[22:23]
	v_lshl_add_u64 v[20:21], v[20:21], 0, v[114:115]
	v_pk_mul_f32 v[22:23], v[22:23], v[36:37]
	s_andn2_b64 vcc, exec, s[38:39]
	v_cvt_pk_bf16_f32 v19, v22, v23
	global_store_dwordx4 v[20:21], v[16:19], off sc0 sc1
	s_mov_b32 s27, 0xa000
	s_nop 0
	v_mov_b32_e32 v16, v155
	v_pk_fma_f32 v[12:13], v[12:13], v[16:17], v[140:141] op_sel_hi:[1,0,1]
	v_pk_fma_f32 v[14:15], v[14:15], v[16:17], v[142:143] op_sel_hi:[1,0,1]
	v_pk_fma_f32 v[8:9], v[8:9], v[16:17], v[136:137] op_sel_hi:[1,0,1]
	v_pk_fma_f32 v[10:11], v[10:11], v[16:17], v[138:139] op_sel_hi:[1,0,1]
	v_pk_mul_f32 v[18:19], v[14:15], s[80:81] op_sel_hi:[1,0]
	v_pk_mul_f32 v[20:21], v[12:13], s[80:81] op_sel_hi:[1,0]
	v_pk_mul_f32 v[22:23], v[10:11], s[80:81] op_sel_hi:[1,0]
	v_pk_mul_f32 v[24:25], v[8:9], s[80:81] op_sel_hi:[1,0]
	v_exp_f32_e32 v20, v20
	v_exp_f32_e32 v21, v21
	v_exp_f32_e32 v18, v18
	v_exp_f32_e32 v19, v19
	v_exp_f32_e32 v24, v24
	v_exp_f32_e32 v25, v25
	v_exp_f32_e32 v22, v22
	v_exp_f32_e32 v23, v23
	v_pk_fma_f32 v[6:7], v[6:7], v[16:17], v[134:135] op_sel_hi:[1,0,1]
	v_pk_fma_f32 v[4:5], v[4:5], v[16:17], v[132:133] op_sel_hi:[1,0,1]
	v_pk_fma_f32 v[2:3], v[2:3], v[16:17], v[130:131] op_sel_hi:[1,0,1]
	v_pk_fma_f32 v[0:1], v[0:1], v[16:17], v[128:129] op_sel_hi:[1,0,1]
	v_pk_add_f32 v[16:17], v[18:19], 1.0 op_sel_hi:[1,0]
	v_pk_add_f32 v[18:19], v[20:21], 1.0 op_sel_hi:[1,0]
	v_pk_add_f32 v[20:21], v[22:23], 1.0 op_sel_hi:[1,0]
	v_pk_add_f32 v[22:23], v[24:25], 1.0 op_sel_hi:[1,0]
	v_rcp_f32_e32 v18, v18
	v_rcp_f32_e32 v19, v19
	v_rcp_f32_e32 v16, v16
	v_rcp_f32_e32 v17, v17
	v_rcp_f32_e32 v22, v22
	v_rcp_f32_e32 v23, v23
	v_rcp_f32_e32 v20, v20
	v_rcp_f32_e32 v21, v21
	v_pk_mul_f32 v[0:1], v[12:13], v[0:1]
	v_pk_mul_f32 v[2:3], v[14:15], v[2:3]
	v_pk_mul_f32 v[4:5], v[8:9], v[4:5]
	v_pk_mul_f32 v[2:3], v[2:3], v[16:17]
	v_pk_mul_f32 v[0:1], v[0:1], v[18:19]
	v_pk_mul_f32 v[4:5], v[4:5], v[22:23]
	v_add_u32_e32 v8, 0xb0, v164
	v_cvt_pk_bf16_f32 v0, v0, v1
	v_cvt_pk_bf16_f32 v1, v2, v3
	v_cvt_pk_bf16_f32 v2, v4, v5
	v_mad_i64_i32 v[4:5], s[22:23], v8, s91, v[112:113]
	v_pk_mul_f32 v[6:7], v[10:11], v[6:7]
	v_lshl_add_u64 v[4:5], v[4:5], 0, v[114:115]
	s_mov_b64 s[22:23], -1
	v_pk_mul_f32 v[6:7], v[6:7], v[20:21]
	s_nop 0
	v_cvt_pk_bf16_f32 v3, v6, v7
	global_store_dwordx4 v[4:5], v[0:3], off sc0 sc1
	s_cbranch_vccnz .LBB0_736
	s_andn2_b64 vcc, exec, s[0:1]
	s_cbranch_vccnz .LBB0_735
	s_barrier
	s_branch .LBB0_735
